# barrier trims + P1 split-K fix-up: each block's 4 partial-tile loads issued together (were load/wait/unpack one at a time)
# baseline (speedup 1.0000x reference)
.LBB0_392:
	global_load_dwordx4 v[232:235], v[124:125], off
	s_mov_b32 s98, 0x20000
	v_add_co_u32_e32 v248, vcc, s98, v124
	s_nop 1
	v_addc_co_u32_e32 v249, vcc, 0, v125, vcc
	global_load_dwordx4 v[236:239], v[248:249], off
	s_mov_b32 s98, 0x40000
	v_add_co_u32_e32 v248, vcc, s98, v124
	s_nop 1
	v_addc_co_u32_e32 v249, vcc, 0, v125, vcc
	global_load_dwordx4 v[240:243], v[248:249], off
	s_mov_b32 s98, 0x60000
	v_add_co_u32_e32 v248, vcc, s98, v124
	s_nop 1
	v_addc_co_u32_e32 v249, vcc, 0, v125, vcc
	global_load_dwordx4 v[244:247], v[248:249], off
	s_waitcnt vmcnt(0)
	s_mov_b32 s2, 0x20000
	v_lshlrev_b32_e32 v6, 16, v232
	v_and_b32_e32 v7, 0xffff0000, v232
	v_lshlrev_b32_e32 v2, 16, v233
	v_and_b32_e32 v3, 0xffff0000, v233
	v_pk_add_f32 v[8:9], v[2:3], 0 op_sel_hi:[1, 0]
	v_lshlrev_b32_e32 v2, 16, v234
	v_and_b32_e32 v3, 0xffff0000, v234
	v_pk_add_f32 v[10:11], v[2:3], 0 op_sel_hi:[1, 0]
	v_lshlrev_b32_e32 v4, 16, v235
	v_and_b32_e32 v5, 0xffff0000, v235
	v_pk_add_f32 v[12:13], v[4:5], 0 op_sel_hi:[1, 0]
	s_mov_b32 s2, 0x40000
	v_pk_add_f32 v[6:7], v[6:7], 0 op_sel_hi:[1, 0]
	v_lshlrev_b32_e32 v14, 16, v236
	v_and_b32_e32 v15, 0xffff0000, v236
	v_lshlrev_b32_e32 v2, 16, v237
	v_and_b32_e32 v3, 0xffff0000, v237
	v_pk_add_f32 v[8:9], v[8:9], v[2:3]
	v_lshlrev_b32_e32 v2, 16, v238
	v_and_b32_e32 v3, 0xffff0000, v238
	v_pk_add_f32 v[10:11], v[10:11], v[2:3]
	v_lshlrev_b32_e32 v4, 16, v239
	v_and_b32_e32 v5, 0xffff0000, v239
	v_pk_add_f32 v[12:13], v[12:13], v[4:5]
	v_pk_add_f32 v[6:7], v[6:7], v[14:15]
	s_mov_b32 s2, 0x60000
	v_lshlrev_b32_e32 v14, 16, v240
	v_and_b32_e32 v15, 0xffff0000, v240
	v_pk_add_f32 v[14:15], v[6:7], v[14:15]
	v_lshlrev_b32_e32 v6, 16, v242
	v_and_b32_e32 v7, 0xffff0000, v242
	v_lshlrev_b32_e32 v4, 16, v243
	v_and_b32_e32 v5, 0xffff0000, v243
	v_pk_add_f32 v[16:17], v[10:11], v[6:7]
	v_pk_add_f32 v[10:11], v[12:13], v[4:5]
	v_lshlrev_b32_e32 v2, 16, v241
	v_and_b32_e32 v3, 0xffff0000, v241
	v_pk_add_f32 v[2:3], v[8:9], v[2:3]
	v_lshlrev_b32_e32 v4, 16, v244
	v_and_b32_e32 v5, 0xffff0000, v244
	v_lshlrev_b32_e32 v6, 16, v245
	v_and_b32_e32 v7, 0xffff0000, v245
	v_pk_add_f32 v[6:7], v[2:3], v[6:7]
	v_lshlrev_b32_e32 v2, 16, v246
	v_and_b32_e32 v3, 0xffff0000, v246
	v_lshlrev_b32_e32 v8, 16, v247
	v_and_b32_e32 v9, 0xffff0000, v247
	v_pk_add_f32 v[4:5], v[14:15], v[4:5]
	v_pk_add_f32 v[10:11], v[10:11], v[8:9]
	v_pk_add_f32 v[8:9], v[16:17], v[2:3]
	v_cndmask_b32_e64 v1, 0, 1, s[70:71]
	v_cmp_ne_u32_e64 s[2:3], 1, v1
	s_andn2_b64 vcc, exec, s[70:71]
	s_cbranch_vccnz .LBB0_390
.LBB0_393:
	global_load_dwordx4 v[232:235], v[124:125], off offset:1024
	s_mov_b32 s98, 0x20000
	v_add_co_u32_e32 v248, vcc, s98, v124
	s_nop 1
	v_addc_co_u32_e32 v249, vcc, 0, v125, vcc
	global_load_dwordx4 v[236:239], v[248:249], off offset:1024
	s_mov_b32 s98, 0x40000
	v_add_co_u32_e32 v248, vcc, s98, v124
	s_nop 1
	v_addc_co_u32_e32 v249, vcc, 0, v125, vcc
	global_load_dwordx4 v[240:243], v[248:249], off offset:1024
	s_mov_b32 s98, 0x60000
	v_add_co_u32_e32 v248, vcc, s98, v124
	s_nop 1
	v_addc_co_u32_e32 v249, vcc, 0, v125, vcc
	global_load_dwordx4 v[244:247], v[248:249], off offset:1024
	s_waitcnt vmcnt(0)
	s_mov_b32 s4, 0x20000
	v_lshlrev_b32_e32 v2, 16, v232
	v_and_b32_e32 v3, 0xffff0000, v232
	v_lshlrev_b32_e32 v12, 16, v233
	v_and_b32_e32 v13, 0xffff0000, v233
	v_pk_add_f32 v[16:17], v[12:13], 0 op_sel_hi:[1, 0]
	v_lshlrev_b32_e32 v12, 16, v234
	v_and_b32_e32 v13, 0xffff0000, v234
	v_pk_add_f32 v[18:19], v[12:13], 0 op_sel_hi:[1, 0]
	v_lshlrev_b32_e32 v14, 16, v235
	v_and_b32_e32 v15, 0xffff0000, v235
	v_pk_add_f32 v[20:21], v[14:15], 0 op_sel_hi:[1, 0]
	s_mov_b32 s4, 0x40000
	v_pk_add_f32 v[2:3], v[2:3], 0 op_sel_hi:[1, 0]
	v_lshlrev_b32_e32 v22, 16, v236
	v_and_b32_e32 v23, 0xffff0000, v236
	v_lshlrev_b32_e32 v12, 16, v237
	v_and_b32_e32 v13, 0xffff0000, v237
	v_pk_add_f32 v[16:17], v[16:17], v[12:13]
	v_lshlrev_b32_e32 v12, 16, v238
	v_and_b32_e32 v13, 0xffff0000, v238
	v_pk_add_f32 v[18:19], v[18:19], v[12:13]
	v_lshlrev_b32_e32 v14, 16, v239
	v_and_b32_e32 v15, 0xffff0000, v239
	v_pk_add_f32 v[20:21], v[20:21], v[14:15]
	v_pk_add_f32 v[2:3], v[2:3], v[22:23]
	s_mov_b32 s4, 0x60000
	v_lshlrev_b32_e32 v22, 16, v240
	v_and_b32_e32 v23, 0xffff0000, v240
	v_lshlrev_b32_e32 v12, 16, v241
	v_and_b32_e32 v13, 0xffff0000, v241
	v_pk_add_f32 v[12:13], v[16:17], v[12:13]
	v_lshlrev_b32_e32 v16, 16, v242
	v_and_b32_e32 v17, 0xffff0000, v242
	v_lshlrev_b32_e32 v14, 16, v243
	v_and_b32_e32 v15, 0xffff0000, v243
	v_pk_add_f32 v[2:3], v[2:3], v[22:23]
	v_pk_add_f32 v[22:23], v[18:19], v[16:17]
	v_pk_add_f32 v[18:19], v[20:21], v[14:15]
	v_lshlrev_b32_e32 v20, 16, v244
	v_and_b32_e32 v21, 0xffff0000, v244
	v_lshlrev_b32_e32 v14, 16, v245
	v_and_b32_e32 v15, 0xffff0000, v245
	v_pk_add_f32 v[14:15], v[12:13], v[14:15]
	v_pk_add_f32 v[12:13], v[2:3], v[20:21]
	v_lshlrev_b32_e32 v2, 16, v246
	v_and_b32_e32 v3, 0xffff0000, v246
	v_lshlrev_b32_e32 v16, 16, v247
	v_and_b32_e32 v17, 0xffff0000, v247
	v_pk_add_f32 v[18:19], v[18:19], v[16:17]
	v_pk_add_f32 v[16:17], v[22:23], v[2:3]
.LBB0_394:
	v_readlane_b32 s6, v255, 3
	v_readlane_b32 s7, v255, 4
	s_andn2_b64 vcc, exec, s[6:7]
	s_nop 0
	v_cndmask_b32_e64 v1, 0, 1, s[6:7]
	v_cmp_ne_u32_e64 s[4:5], 1, v1
	s_cbranch_vccnz .LBB0_397
	global_load_dwordx4 v[232:235], v[124:125], off offset:2048
	s_mov_b32 s98, 0x20000
	v_add_co_u32_e32 v248, vcc, s98, v124
	s_nop 1
	v_addc_co_u32_e32 v249, vcc, 0, v125, vcc
	global_load_dwordx4 v[236:239], v[248:249], off offset:2048
	s_mov_b32 s98, 0x40000
	v_add_co_u32_e32 v248, vcc, s98, v124
	s_nop 1
	v_addc_co_u32_e32 v249, vcc, 0, v125, vcc
	global_load_dwordx4 v[240:243], v[248:249], off offset:2048
	s_mov_b32 s98, 0x60000
	v_add_co_u32_e32 v248, vcc, s98, v124
	s_nop 1
	v_addc_co_u32_e32 v249, vcc, 0, v125, vcc
	global_load_dwordx4 v[244:247], v[248:249], off offset:2048
	s_waitcnt vmcnt(0)
	s_mov_b32 s6, 0x20000
	v_lshlrev_b32_e32 v2, 16, v232
	v_and_b32_e32 v3, 0xffff0000, v232
	v_lshlrev_b32_e32 v20, 16, v233
	v_and_b32_e32 v21, 0xffff0000, v233
	v_pk_add_f32 v[24:25], v[20:21], 0 op_sel_hi:[1, 0]
	v_lshlrev_b32_e32 v20, 16, v234
	v_and_b32_e32 v21, 0xffff0000, v234
	v_pk_add_f32 v[26:27], v[20:21], 0 op_sel_hi:[1, 0]
	v_lshlrev_b32_e32 v22, 16, v235
	v_and_b32_e32 v23, 0xffff0000, v235
	v_pk_add_f32 v[28:29], v[22:23], 0 op_sel_hi:[1, 0]
	s_mov_b32 s6, 0x40000
	v_pk_add_f32 v[2:3], v[2:3], 0 op_sel_hi:[1, 0]
	v_lshlrev_b32_e32 v30, 16, v236
	v_and_b32_e32 v31, 0xffff0000, v236
	v_lshlrev_b32_e32 v20, 16, v237
	v_and_b32_e32 v21, 0xffff0000, v237
	v_pk_add_f32 v[24:25], v[24:25], v[20:21]
	v_lshlrev_b32_e32 v20, 16, v238
	v_and_b32_e32 v21, 0xffff0000, v238
	v_pk_add_f32 v[26:27], v[26:27], v[20:21]
	v_lshlrev_b32_e32 v22, 16, v239
	v_and_b32_e32 v23, 0xffff0000, v239
	v_pk_add_f32 v[28:29], v[28:29], v[22:23]
	v_pk_add_f32 v[2:3], v[2:3], v[30:31]
	s_mov_b32 s6, 0x60000
	v_lshlrev_b32_e32 v30, 16, v240
	v_and_b32_e32 v31, 0xffff0000, v240
	v_lshlrev_b32_e32 v20, 16, v241
	v_and_b32_e32 v21, 0xffff0000, v241
	v_pk_add_f32 v[20:21], v[24:25], v[20:21]
	v_lshlrev_b32_e32 v24, 16, v242
	v_and_b32_e32 v25, 0xffff0000, v242
	v_lshlrev_b32_e32 v22, 16, v243
	v_and_b32_e32 v23, 0xffff0000, v243
	v_pk_add_f32 v[2:3], v[2:3], v[30:31]
	v_pk_add_f32 v[30:31], v[26:27], v[24:25]
	v_pk_add_f32 v[26:27], v[28:29], v[22:23]
	v_lshlrev_b32_e32 v28, 16, v244
	v_and_b32_e32 v29, 0xffff0000, v244
	v_lshlrev_b32_e32 v22, 16, v245
	v_and_b32_e32 v23, 0xffff0000, v245
	v_pk_add_f32 v[22:23], v[20:21], v[22:23]
	v_pk_add_f32 v[20:21], v[2:3], v[28:29]
	v_lshlrev_b32_e32 v2, 16, v246
	v_and_b32_e32 v3, 0xffff0000, v246
	v_lshlrev_b32_e32 v24, 16, v247
	v_and_b32_e32 v25, 0xffff0000, v247
	v_pk_add_f32 v[26:27], v[26:27], v[24:25]
	v_pk_add_f32 v[24:25], v[30:31], v[2:3]
	s_and_b64 vcc, exec, s[4:5]
	s_cbranch_vccz .LBB0_398

.LBB0_398:
	global_load_dwordx4 v[232:235], v[124:125], off offset:3072
	s_mov_b32 s98, 0x20000
	v_add_co_u32_e32 v248, vcc, s98, v124
	s_nop 1
	v_addc_co_u32_e32 v249, vcc, 0, v125, vcc
	global_load_dwordx4 v[236:239], v[248:249], off offset:3072
	s_mov_b32 s98, 0x40000
	v_add_co_u32_e32 v248, vcc, s98, v124
	s_nop 1
	v_addc_co_u32_e32 v249, vcc, 0, v125, vcc
	global_load_dwordx4 v[240:243], v[248:249], off offset:3072
	s_mov_b32 s98, 0x60000
	v_add_co_u32_e32 v248, vcc, s98, v124
	s_nop 1
	v_addc_co_u32_e32 v249, vcc, 0, v125, vcc
	global_load_dwordx4 v[244:247], v[248:249], off offset:3072
	s_waitcnt vmcnt(0)
	s_mov_b32 s6, 0x20000
	v_lshlrev_b32_e32 v2, 16, v232
	v_and_b32_e32 v3, 0xffff0000, v232
	v_lshlrev_b32_e32 v28, 16, v233
	v_and_b32_e32 v29, 0xffff0000, v233
	v_pk_add_f32 v[32:33], v[28:29], 0 op_sel_hi:[1, 0]
	v_lshlrev_b32_e32 v28, 16, v234
	v_and_b32_e32 v29, 0xffff0000, v234
	v_pk_add_f32 v[34:35], v[28:29], 0 op_sel_hi:[1, 0]
	v_lshlrev_b32_e32 v30, 16, v235
	v_and_b32_e32 v31, 0xffff0000, v235
	v_pk_add_f32 v[36:37], v[30:31], 0 op_sel_hi:[1, 0]
	s_mov_b32 s6, 0x40000
	v_pk_add_f32 v[2:3], v[2:3], 0 op_sel_hi:[1, 0]
	v_lshlrev_b32_e32 v38, 16, v236
	v_and_b32_e32 v39, 0xffff0000, v236
	v_lshlrev_b32_e32 v28, 16, v237
	v_and_b32_e32 v29, 0xffff0000, v237
	v_pk_add_f32 v[32:33], v[32:33], v[28:29]
	v_lshlrev_b32_e32 v28, 16, v238
	v_and_b32_e32 v29, 0xffff0000, v238
	v_pk_add_f32 v[34:35], v[34:35], v[28:29]
	v_lshlrev_b32_e32 v30, 16, v239
	v_and_b32_e32 v31, 0xffff0000, v239
	v_pk_add_f32 v[36:37], v[36:37], v[30:31]
	v_pk_add_f32 v[2:3], v[2:3], v[38:39]
	s_mov_b32 s6, 0x60000
	v_lshlrev_b32_e32 v38, 16, v240
	v_and_b32_e32 v39, 0xffff0000, v240
	v_lshlrev_b32_e32 v28, 16, v241
	v_and_b32_e32 v29, 0xffff0000, v241
	v_pk_add_f32 v[28:29], v[32:33], v[28:29]
	v_lshlrev_b32_e32 v32, 16, v242
	v_and_b32_e32 v33, 0xffff0000, v242
	v_lshlrev_b32_e32 v30, 16, v243
	v_and_b32_e32 v31, 0xffff0000, v243
	v_pk_add_f32 v[2:3], v[2:3], v[38:39]
	v_pk_add_f32 v[38:39], v[34:35], v[32:33]
	v_pk_add_f32 v[34:35], v[36:37], v[30:31]
	v_lshlrev_b32_e32 v36, 16, v244
	v_and_b32_e32 v37, 0xffff0000, v244
	v_lshlrev_b32_e32 v30, 16, v245
	v_and_b32_e32 v31, 0xffff0000, v245
	v_pk_add_f32 v[30:31], v[28:29], v[30:31]
	v_pk_add_f32 v[28:29], v[2:3], v[36:37]
	v_lshlrev_b32_e32 v2, 16, v246
	v_and_b32_e32 v3, 0xffff0000, v246
	v_lshlrev_b32_e32 v32, 16, v247
	v_and_b32_e32 v33, 0xffff0000, v247
	v_pk_add_f32 v[34:35], v[34:35], v[32:33]
	v_pk_add_f32 v[32:33], v[38:39], v[2:3]
.LBB0_399:
	v_readlane_b32 s8, v255, 5
	v_readlane_b32 s9, v255, 6
	s_andn2_b64 vcc, exec, s[8:9]
	s_nop 0
	v_cndmask_b32_e64 v1, 0, 1, s[8:9]
	v_cmp_ne_u32_e64 s[6:7], 1, v1
	s_cbranch_vccnz .LBB0_402
	v_add_co_u32_e32 v2, vcc, 0x1000, v124
	s_nop 1
	v_addc_co_u32_e32 v3, vcc, 0, v125, vcc
	global_load_dwordx4 v[232:235], v[2:3], off
	v_add_co_u32_e32 v248, vcc, s21, v124
	s_nop 1
	v_addc_co_u32_e32 v249, vcc, 0, v125, vcc
	global_load_dwordx4 v[236:239], v[248:249], off
	v_add_co_u32_e32 v248, vcc, s22, v124
	s_nop 1
	v_addc_co_u32_e32 v249, vcc, 0, v125, vcc
	global_load_dwordx4 v[240:243], v[248:249], off
	v_add_co_u32_e32 v248, vcc, s23, v124
	s_nop 1
	v_addc_co_u32_e32 v249, vcc, 0, v125, vcc
	global_load_dwordx4 v[244:247], v[248:249], off
	s_waitcnt vmcnt(0)
	v_lshlrev_b32_e32 v2, 16, v232
	v_and_b32_e32 v3, 0xffff0000, v232
	v_lshlrev_b32_e32 v36, 16, v233
	v_and_b32_e32 v37, 0xffff0000, v233
	v_pk_add_f32 v[40:41], v[36:37], 0 op_sel_hi:[1, 0]
	v_lshlrev_b32_e32 v36, 16, v234
	v_and_b32_e32 v37, 0xffff0000, v234
	v_pk_add_f32 v[42:43], v[36:37], 0 op_sel_hi:[1, 0]
	v_lshlrev_b32_e32 v38, 16, v235
	v_and_b32_e32 v39, 0xffff0000, v235
	v_pk_add_f32 v[44:45], v[38:39], 0 op_sel_hi:[1, 0]
	v_pk_add_f32 v[2:3], v[2:3], 0 op_sel_hi:[1, 0]
	v_lshlrev_b32_e32 v46, 16, v236
	v_and_b32_e32 v47, 0xffff0000, v236
	v_lshlrev_b32_e32 v36, 16, v237
	v_and_b32_e32 v37, 0xffff0000, v237
	v_pk_add_f32 v[40:41], v[40:41], v[36:37]
	v_lshlrev_b32_e32 v36, 16, v238
	v_and_b32_e32 v37, 0xffff0000, v238
	v_pk_add_f32 v[42:43], v[42:43], v[36:37]
	v_lshlrev_b32_e32 v38, 16, v239
	v_and_b32_e32 v39, 0xffff0000, v239
	v_pk_add_f32 v[44:45], v[44:45], v[38:39]
	v_pk_add_f32 v[2:3], v[2:3], v[46:47]
	v_lshlrev_b32_e32 v46, 16, v240
	v_and_b32_e32 v47, 0xffff0000, v240
	v_lshlrev_b32_e32 v36, 16, v241
	v_and_b32_e32 v37, 0xffff0000, v241
	v_pk_add_f32 v[46:47], v[2:3], v[46:47]
	v_lshlrev_b32_e32 v2, 16, v242
	v_and_b32_e32 v3, 0xffff0000, v242
	v_lshlrev_b32_e32 v38, 16, v243
	v_and_b32_e32 v39, 0xffff0000, v243
	v_pk_add_f32 v[36:37], v[40:41], v[36:37]
	v_pk_add_f32 v[40:41], v[44:45], v[38:39]
	v_pk_add_f32 v[2:3], v[42:43], v[2:3]
	v_lshlrev_b32_e32 v48, 16, v244
	v_and_b32_e32 v49, 0xffff0000, v244
	v_lshlrev_b32_e32 v38, 16, v245
	v_and_b32_e32 v39, 0xffff0000, v245
	v_pk_add_f32 v[38:39], v[36:37], v[38:39]
	v_pk_add_f32 v[36:37], v[46:47], v[48:49]
	v_lshlrev_b32_e32 v46, 16, v246
	v_and_b32_e32 v47, 0xffff0000, v246
	v_lshlrev_b32_e32 v42, 16, v247
	v_and_b32_e32 v43, 0xffff0000, v247
	v_pk_add_f32 v[42:43], v[40:41], v[42:43]
	v_pk_add_f32 v[40:41], v[2:3], v[46:47]
	s_and_b64 vcc, exec, s[6:7]
	s_cbranch_vccz .LBB0_403

.LBB0_403:
	v_add_co_u32_e32 v2, vcc, 0x1000, v124
	s_nop 1
	v_addc_co_u32_e32 v3, vcc, 0, v125, vcc
	global_load_dwordx4 v[232:235], v[2:3], off offset:1024
	v_add_co_u32_e32 v248, vcc, s21, v124
	s_nop 1
	v_addc_co_u32_e32 v249, vcc, 0, v125, vcc
	global_load_dwordx4 v[236:239], v[248:249], off offset:1024
	v_add_co_u32_e32 v248, vcc, s22, v124
	s_nop 1
	v_addc_co_u32_e32 v249, vcc, 0, v125, vcc
	global_load_dwordx4 v[240:243], v[248:249], off offset:1024
	v_add_co_u32_e32 v248, vcc, s23, v124
	s_nop 1
	v_addc_co_u32_e32 v249, vcc, 0, v125, vcc
	global_load_dwordx4 v[244:247], v[248:249], off offset:1024
	s_waitcnt vmcnt(0)
	v_lshlrev_b32_e32 v2, 16, v232
	v_and_b32_e32 v3, 0xffff0000, v232
	v_lshlrev_b32_e32 v44, 16, v233
	v_and_b32_e32 v45, 0xffff0000, v233
	v_pk_add_f32 v[48:49], v[44:45], 0 op_sel_hi:[1, 0]
	v_lshlrev_b32_e32 v44, 16, v234
	v_and_b32_e32 v45, 0xffff0000, v234
	v_pk_add_f32 v[50:51], v[44:45], 0 op_sel_hi:[1, 0]
	v_lshlrev_b32_e32 v46, 16, v235
	v_and_b32_e32 v47, 0xffff0000, v235
	v_pk_add_f32 v[52:53], v[46:47], 0 op_sel_hi:[1, 0]
	v_pk_add_f32 v[2:3], v[2:3], 0 op_sel_hi:[1, 0]
	v_lshlrev_b32_e32 v54, 16, v236
	v_and_b32_e32 v55, 0xffff0000, v236
	v_lshlrev_b32_e32 v44, 16, v237
	v_and_b32_e32 v45, 0xffff0000, v237
	v_pk_add_f32 v[48:49], v[48:49], v[44:45]
	v_lshlrev_b32_e32 v44, 16, v238
	v_and_b32_e32 v45, 0xffff0000, v238
	v_pk_add_f32 v[50:51], v[50:51], v[44:45]
	v_lshlrev_b32_e32 v46, 16, v239
	v_and_b32_e32 v47, 0xffff0000, v239
	v_pk_add_f32 v[52:53], v[52:53], v[46:47]
	v_pk_add_f32 v[2:3], v[2:3], v[54:55]
	v_lshlrev_b32_e32 v54, 16, v240
	v_and_b32_e32 v55, 0xffff0000, v240
	v_lshlrev_b32_e32 v44, 16, v241
	v_and_b32_e32 v45, 0xffff0000, v241
	v_pk_add_f32 v[54:55], v[2:3], v[54:55]
	v_lshlrev_b32_e32 v2, 16, v242
	v_and_b32_e32 v3, 0xffff0000, v242
	v_lshlrev_b32_e32 v46, 16, v243
	v_and_b32_e32 v47, 0xffff0000, v243
	v_pk_add_f32 v[44:45], v[48:49], v[44:45]
	v_pk_add_f32 v[48:49], v[52:53], v[46:47]
	v_pk_add_f32 v[2:3], v[50:51], v[2:3]
	v_lshlrev_b32_e32 v56, 16, v244
	v_and_b32_e32 v57, 0xffff0000, v244
	v_lshlrev_b32_e32 v46, 16, v245
	v_and_b32_e32 v47, 0xffff0000, v245
	v_pk_add_f32 v[46:47], v[44:45], v[46:47]
	v_pk_add_f32 v[44:45], v[54:55], v[56:57]
	v_lshlrev_b32_e32 v54, 16, v246
	v_and_b32_e32 v55, 0xffff0000, v246
	v_lshlrev_b32_e32 v50, 16, v247
	v_and_b32_e32 v51, 0xffff0000, v247
	v_pk_add_f32 v[50:51], v[48:49], v[50:51]
	v_pk_add_f32 v[48:49], v[2:3], v[54:55]
.LBB0_404:
	v_readlane_b32 s10, v255, 7
	v_readlane_b32 s11, v255, 8
	s_andn2_b64 vcc, exec, s[10:11]
	s_nop 0
	v_cndmask_b32_e64 v1, 0, 1, s[10:11]
	v_cmp_ne_u32_e64 s[8:9], 1, v1
	s_cbranch_vccnz .LBB0_409
	v_add_co_u32_e32 v2, vcc, 0x1000, v124
	s_nop 1
	v_addc_co_u32_e32 v3, vcc, 0, v125, vcc
	global_load_dwordx4 v[232:235], v[2:3], off offset:2048
	v_add_co_u32_e32 v248, vcc, s21, v124
	s_nop 1
	v_addc_co_u32_e32 v249, vcc, 0, v125, vcc
	global_load_dwordx4 v[236:239], v[248:249], off offset:2048
	v_add_co_u32_e32 v248, vcc, s22, v124
	s_nop 1
	v_addc_co_u32_e32 v249, vcc, 0, v125, vcc
	global_load_dwordx4 v[240:243], v[248:249], off offset:2048
	v_add_co_u32_e32 v248, vcc, s23, v124
	s_nop 1
	v_addc_co_u32_e32 v249, vcc, 0, v125, vcc
	global_load_dwordx4 v[244:247], v[248:249], off offset:2048
	s_waitcnt vmcnt(0)
	v_lshlrev_b32_e32 v2, 16, v232
	v_and_b32_e32 v3, 0xffff0000, v232
	v_lshlrev_b32_e32 v52, 16, v233
	v_and_b32_e32 v53, 0xffff0000, v233
	v_pk_add_f32 v[56:57], v[52:53], 0 op_sel_hi:[1, 0]
	v_lshlrev_b32_e32 v52, 16, v234
	v_and_b32_e32 v53, 0xffff0000, v234
	v_pk_add_f32 v[58:59], v[52:53], 0 op_sel_hi:[1, 0]
	v_lshlrev_b32_e32 v54, 16, v235
	v_and_b32_e32 v55, 0xffff0000, v235
	v_pk_add_f32 v[60:61], v[54:55], 0 op_sel_hi:[1, 0]
	v_pk_add_f32 v[2:3], v[2:3], 0 op_sel_hi:[1, 0]
	v_lshlrev_b32_e32 v62, 16, v236
	v_and_b32_e32 v63, 0xffff0000, v236
	v_lshlrev_b32_e32 v52, 16, v237
	v_and_b32_e32 v53, 0xffff0000, v237
	v_pk_add_f32 v[56:57], v[56:57], v[52:53]
	v_lshlrev_b32_e32 v52, 16, v238
	v_and_b32_e32 v53, 0xffff0000, v238
	v_pk_add_f32 v[58:59], v[58:59], v[52:53]
	v_lshlrev_b32_e32 v54, 16, v239
	v_and_b32_e32 v55, 0xffff0000, v239
	v_pk_add_f32 v[60:61], v[60:61], v[54:55]
	v_pk_add_f32 v[2:3], v[2:3], v[62:63]
	v_lshlrev_b32_e32 v62, 16, v240
	v_and_b32_e32 v63, 0xffff0000, v240
	v_lshlrev_b32_e32 v52, 16, v241
	v_and_b32_e32 v53, 0xffff0000, v241
	v_pk_add_f32 v[62:63], v[2:3], v[62:63]
	v_lshlrev_b32_e32 v2, 16, v242
	v_and_b32_e32 v3, 0xffff0000, v242
	v_lshlrev_b32_e32 v54, 16, v243
	v_and_b32_e32 v55, 0xffff0000, v243
	v_pk_add_f32 v[52:53], v[56:57], v[52:53]
	v_pk_add_f32 v[56:57], v[60:61], v[54:55]
	v_pk_add_f32 v[2:3], v[58:59], v[2:3]
	v_lshlrev_b32_e32 v64, 16, v244
	v_and_b32_e32 v65, 0xffff0000, v244
	v_lshlrev_b32_e32 v54, 16, v245
	v_and_b32_e32 v55, 0xffff0000, v245
	v_pk_add_f32 v[54:55], v[52:53], v[54:55]
	v_pk_add_f32 v[52:53], v[62:63], v[64:65]
	v_lshlrev_b32_e32 v62, 16, v246
	v_and_b32_e32 v63, 0xffff0000, v246
	v_lshlrev_b32_e32 v58, 16, v247
	v_and_b32_e32 v59, 0xffff0000, v247
	v_pk_add_f32 v[58:59], v[56:57], v[58:59]
	v_pk_add_f32 v[56:57], v[2:3], v[62:63]
	s_and_b64 vcc, exec, s[8:9]
	s_cbranch_vccz .LBB0_410

.LBB0_410:
	v_add_co_u32_e32 v2, vcc, 0x1000, v124
	s_nop 1
	v_addc_co_u32_e32 v3, vcc, 0, v125, vcc
	global_load_dwordx4 v[232:235], v[2:3], off offset:3072
	v_add_co_u32_e32 v248, vcc, s21, v124
	s_nop 1
	v_addc_co_u32_e32 v249, vcc, 0, v125, vcc
	global_load_dwordx4 v[236:239], v[248:249], off offset:3072
	v_add_co_u32_e32 v248, vcc, s22, v124
	s_nop 1
	v_addc_co_u32_e32 v249, vcc, 0, v125, vcc
	global_load_dwordx4 v[240:243], v[248:249], off offset:3072
	v_add_co_u32_e32 v248, vcc, s23, v124
	s_nop 1
	v_addc_co_u32_e32 v249, vcc, 0, v125, vcc
	global_load_dwordx4 v[244:247], v[248:249], off offset:3072
	s_waitcnt vmcnt(0)
	v_lshlrev_b32_e32 v2, 16, v232
	v_and_b32_e32 v3, 0xffff0000, v232
	v_lshlrev_b32_e32 v60, 16, v233
	v_and_b32_e32 v61, 0xffff0000, v233
	v_pk_add_f32 v[64:65], v[60:61], 0 op_sel_hi:[1, 0]
	v_lshlrev_b32_e32 v60, 16, v234
	v_and_b32_e32 v61, 0xffff0000, v234
	v_pk_add_f32 v[66:67], v[60:61], 0 op_sel_hi:[1, 0]
	v_lshlrev_b32_e32 v62, 16, v235
	v_and_b32_e32 v63, 0xffff0000, v235
	v_pk_add_f32 v[68:69], v[62:63], 0 op_sel_hi:[1, 0]
	v_pk_add_f32 v[2:3], v[2:3], 0 op_sel_hi:[1, 0]
	v_lshlrev_b32_e32 v70, 16, v236
	v_and_b32_e32 v71, 0xffff0000, v236
	v_lshlrev_b32_e32 v60, 16, v237
	v_and_b32_e32 v61, 0xffff0000, v237
	v_pk_add_f32 v[64:65], v[64:65], v[60:61]
	v_lshlrev_b32_e32 v60, 16, v238
	v_and_b32_e32 v61, 0xffff0000, v238
	v_pk_add_f32 v[66:67], v[66:67], v[60:61]
	v_lshlrev_b32_e32 v62, 16, v239
	v_and_b32_e32 v63, 0xffff0000, v239
	v_pk_add_f32 v[68:69], v[68:69], v[62:63]
	v_pk_add_f32 v[2:3], v[2:3], v[70:71]
	v_lshlrev_b32_e32 v70, 16, v240
	v_and_b32_e32 v71, 0xffff0000, v240
	v_lshlrev_b32_e32 v60, 16, v241
	v_and_b32_e32 v61, 0xffff0000, v241
	v_pk_add_f32 v[70:71], v[2:3], v[70:71]
	v_lshlrev_b32_e32 v2, 16, v242
	v_and_b32_e32 v3, 0xffff0000, v242
	v_lshlrev_b32_e32 v62, 16, v243
	v_and_b32_e32 v63, 0xffff0000, v243
	v_pk_add_f32 v[60:61], v[64:65], v[60:61]
	v_pk_add_f32 v[64:65], v[68:69], v[62:63]
	v_pk_add_f32 v[2:3], v[66:67], v[2:3]
	v_lshlrev_b32_e32 v72, 16, v244
	v_and_b32_e32 v73, 0xffff0000, v244
	v_lshlrev_b32_e32 v62, 16, v245
	v_and_b32_e32 v63, 0xffff0000, v245
	v_pk_add_f32 v[62:63], v[60:61], v[62:63]
	v_pk_add_f32 v[60:61], v[70:71], v[72:73]
	v_lshlrev_b32_e32 v70, 16, v246
	v_and_b32_e32 v71, 0xffff0000, v246
	v_lshlrev_b32_e32 v66, 16, v247
	v_and_b32_e32 v67, 0xffff0000, v247
	v_pk_add_f32 v[66:67], v[64:65], v[66:67]
	v_pk_add_f32 v[64:65], v[2:3], v[70:71]
	s_and_b64 vcc, exec, s[2:3]
	s_cbranch_vccnz .LBB0_407
.LBB0_411:
	v_add_co_u32_e32 v2, vcc, 0x2000, v124
	s_mov_b32 s10, 0x22000
	s_nop 0
	v_addc_co_u32_e32 v3, vcc, 0, v125, vcc
	global_load_dwordx4 v[232:235], v[2:3], off
	v_add_co_u32_e32 v248, vcc, s10, v124
	s_nop 1
	v_addc_co_u32_e32 v249, vcc, 0, v125, vcc
	global_load_dwordx4 v[236:239], v[248:249], off
	s_mov_b32 s98, 0x42000
	v_add_co_u32_e32 v248, vcc, s98, v124
	s_nop 1
	v_addc_co_u32_e32 v249, vcc, 0, v125, vcc
	global_load_dwordx4 v[240:243], v[248:249], off
	s_mov_b32 s98, 0x62000
	v_add_co_u32_e32 v248, vcc, s98, v124
	s_nop 1
	v_addc_co_u32_e32 v249, vcc, 0, v125, vcc
	global_load_dwordx4 v[244:247], v[248:249], off
	s_waitcnt vmcnt(0)
	v_lshlrev_b32_e32 v2, 16, v232
	v_and_b32_e32 v3, 0xffff0000, v232
	v_lshlrev_b32_e32 v68, 16, v233
	v_and_b32_e32 v69, 0xffff0000, v233
	v_pk_add_f32 v[72:73], v[68:69], 0 op_sel_hi:[1, 0]
	v_lshlrev_b32_e32 v68, 16, v234
	v_and_b32_e32 v69, 0xffff0000, v234
	v_pk_add_f32 v[74:75], v[68:69], 0 op_sel_hi:[1, 0]
	v_lshlrev_b32_e32 v70, 16, v235
	v_and_b32_e32 v71, 0xffff0000, v235
	v_pk_add_f32 v[76:77], v[70:71], 0 op_sel_hi:[1, 0]
	s_mov_b32 s10, 0x42000
	v_pk_add_f32 v[2:3], v[2:3], 0 op_sel_hi:[1, 0]
	v_lshlrev_b32_e32 v78, 16, v236
	v_and_b32_e32 v79, 0xffff0000, v236
	v_lshlrev_b32_e32 v68, 16, v237
	v_and_b32_e32 v69, 0xffff0000, v237
	v_pk_add_f32 v[72:73], v[72:73], v[68:69]
	v_lshlrev_b32_e32 v68, 16, v238
	v_and_b32_e32 v69, 0xffff0000, v238
	v_pk_add_f32 v[74:75], v[74:75], v[68:69]
	v_lshlrev_b32_e32 v70, 16, v239
	v_and_b32_e32 v71, 0xffff0000, v239
	v_pk_add_f32 v[76:77], v[76:77], v[70:71]
	v_pk_add_f32 v[2:3], v[2:3], v[78:79]
	s_mov_b32 s10, 0x62000
	v_lshlrev_b32_e32 v78, 16, v240
	v_and_b32_e32 v79, 0xffff0000, v240
	v_lshlrev_b32_e32 v68, 16, v241
	v_and_b32_e32 v69, 0xffff0000, v241
	v_pk_add_f32 v[78:79], v[2:3], v[78:79]
	v_lshlrev_b32_e32 v2, 16, v242
	v_and_b32_e32 v3, 0xffff0000, v242
	v_lshlrev_b32_e32 v70, 16, v243
	v_and_b32_e32 v71, 0xffff0000, v243
	v_pk_add_f32 v[68:69], v[72:73], v[68:69]
	v_pk_add_f32 v[72:73], v[76:77], v[70:71]
	v_pk_add_f32 v[2:3], v[74:75], v[2:3]
	v_lshlrev_b32_e32 v80, 16, v244
	v_and_b32_e32 v81, 0xffff0000, v244
	v_lshlrev_b32_e32 v70, 16, v245
	v_and_b32_e32 v71, 0xffff0000, v245
	v_pk_add_f32 v[70:71], v[68:69], v[70:71]
	v_pk_add_f32 v[68:69], v[78:79], v[80:81]
	v_lshlrev_b32_e32 v78, 16, v246
	v_and_b32_e32 v79, 0xffff0000, v246
	v_lshlrev_b32_e32 v74, 16, v247
	v_and_b32_e32 v75, 0xffff0000, v247
	v_pk_add_f32 v[74:75], v[72:73], v[74:75]
	v_pk_add_f32 v[72:73], v[2:3], v[78:79]
	s_and_b64 vcc, exec, s[2:3]
	s_cbranch_vccnz .LBB0_408
.LBB0_412:
	v_add_co_u32_e32 v2, vcc, 0x2000, v124
	s_mov_b32 s10, 0x22000
	s_nop 0
	v_addc_co_u32_e32 v3, vcc, 0, v125, vcc
	global_load_dwordx4 v[232:235], v[2:3], off offset:1024
	v_add_co_u32_e32 v248, vcc, s10, v124
	s_nop 1
	v_addc_co_u32_e32 v249, vcc, 0, v125, vcc
	global_load_dwordx4 v[236:239], v[248:249], off offset:1024
	s_mov_b32 s98, 0x42000
	v_add_co_u32_e32 v248, vcc, s98, v124
	s_nop 1
	v_addc_co_u32_e32 v249, vcc, 0, v125, vcc
	global_load_dwordx4 v[240:243], v[248:249], off offset:1024
	s_mov_b32 s98, 0x62000
	v_add_co_u32_e32 v248, vcc, s98, v124
	s_nop 1
	v_addc_co_u32_e32 v249, vcc, 0, v125, vcc
	global_load_dwordx4 v[244:247], v[248:249], off offset:1024
	s_waitcnt vmcnt(0)
	v_lshlrev_b32_e32 v2, 16, v232
	v_and_b32_e32 v3, 0xffff0000, v232
	v_lshlrev_b32_e32 v76, 16, v233
	v_and_b32_e32 v77, 0xffff0000, v233
	v_pk_add_f32 v[80:81], v[76:77], 0 op_sel_hi:[1, 0]
	v_lshlrev_b32_e32 v76, 16, v234
	v_and_b32_e32 v77, 0xffff0000, v234
	v_pk_add_f32 v[82:83], v[76:77], 0 op_sel_hi:[1, 0]
	v_lshlrev_b32_e32 v78, 16, v235
	v_and_b32_e32 v79, 0xffff0000, v235
	v_pk_add_f32 v[84:85], v[78:79], 0 op_sel_hi:[1, 0]
	s_mov_b32 s10, 0x42000
	v_pk_add_f32 v[2:3], v[2:3], 0 op_sel_hi:[1, 0]
	v_lshlrev_b32_e32 v86, 16, v236
	v_and_b32_e32 v87, 0xffff0000, v236
	v_lshlrev_b32_e32 v76, 16, v237
	v_and_b32_e32 v77, 0xffff0000, v237
	v_pk_add_f32 v[80:81], v[80:81], v[76:77]
	v_lshlrev_b32_e32 v76, 16, v238
	v_and_b32_e32 v77, 0xffff0000, v238
	v_pk_add_f32 v[82:83], v[82:83], v[76:77]
	v_lshlrev_b32_e32 v78, 16, v239
	v_and_b32_e32 v79, 0xffff0000, v239
	v_pk_add_f32 v[84:85], v[84:85], v[78:79]
	v_pk_add_f32 v[2:3], v[2:3], v[86:87]
	s_mov_b32 s10, 0x62000
	v_lshlrev_b32_e32 v86, 16, v240
	v_and_b32_e32 v87, 0xffff0000, v240
	v_lshlrev_b32_e32 v76, 16, v241
	v_and_b32_e32 v77, 0xffff0000, v241
	v_pk_add_f32 v[86:87], v[2:3], v[86:87]
	v_lshlrev_b32_e32 v2, 16, v242
	v_and_b32_e32 v3, 0xffff0000, v242
	v_lshlrev_b32_e32 v78, 16, v243
	v_and_b32_e32 v79, 0xffff0000, v243
	v_pk_add_f32 v[76:77], v[80:81], v[76:77]
	v_pk_add_f32 v[80:81], v[84:85], v[78:79]
	v_pk_add_f32 v[2:3], v[82:83], v[2:3]
	v_lshlrev_b32_e32 v88, 16, v244
	v_and_b32_e32 v89, 0xffff0000, v244
	v_lshlrev_b32_e32 v78, 16, v245
	v_and_b32_e32 v79, 0xffff0000, v245
	v_pk_add_f32 v[78:79], v[76:77], v[78:79]
	v_pk_add_f32 v[76:77], v[86:87], v[88:89]
	v_lshlrev_b32_e32 v86, 16, v246
	v_and_b32_e32 v87, 0xffff0000, v246
	v_lshlrev_b32_e32 v82, 16, v247
	v_and_b32_e32 v83, 0xffff0000, v247
	v_pk_add_f32 v[82:83], v[80:81], v[82:83]
	v_pk_add_f32 v[80:81], v[2:3], v[86:87]
.LBB0_413:
	v_readlane_b32 s12, v255, 9
	v_readlane_b32 s13, v255, 10
	s_andn2_b64 vcc, exec, s[12:13]
	s_nop 0
	v_cndmask_b32_e64 v1, 0, 1, s[12:13]
	v_cmp_ne_u32_e64 s[10:11], 1, v1
	s_cbranch_vccnz .LBB0_416
	v_add_co_u32_e32 v2, vcc, 0x2000, v124
	s_mov_b32 s12, 0x22000
	s_nop 0
	v_addc_co_u32_e32 v3, vcc, 0, v125, vcc
	global_load_dwordx4 v[232:235], v[2:3], off offset:2048
	v_add_co_u32_e32 v248, vcc, s12, v124
	s_nop 1
	v_addc_co_u32_e32 v249, vcc, 0, v125, vcc
	global_load_dwordx4 v[236:239], v[248:249], off offset:2048
	s_mov_b32 s98, 0x42000
	v_add_co_u32_e32 v248, vcc, s98, v124
	s_nop 1
	v_addc_co_u32_e32 v249, vcc, 0, v125, vcc
	global_load_dwordx4 v[240:243], v[248:249], off offset:2048
	s_mov_b32 s98, 0x62000
	v_add_co_u32_e32 v248, vcc, s98, v124
	s_nop 1
	v_addc_co_u32_e32 v249, vcc, 0, v125, vcc
	global_load_dwordx4 v[244:247], v[248:249], off offset:2048
	s_waitcnt vmcnt(0)
	v_lshlrev_b32_e32 v2, 16, v232
	v_and_b32_e32 v3, 0xffff0000, v232
	v_lshlrev_b32_e32 v84, 16, v233
	v_and_b32_e32 v85, 0xffff0000, v233
	v_pk_add_f32 v[88:89], v[84:85], 0 op_sel_hi:[1, 0]
	v_lshlrev_b32_e32 v84, 16, v234
	v_and_b32_e32 v85, 0xffff0000, v234
	v_pk_add_f32 v[90:91], v[84:85], 0 op_sel_hi:[1, 0]
	v_lshlrev_b32_e32 v86, 16, v235
	v_and_b32_e32 v87, 0xffff0000, v235
	v_pk_add_f32 v[92:93], v[86:87], 0 op_sel_hi:[1, 0]
	s_mov_b32 s12, 0x42000
	v_pk_add_f32 v[2:3], v[2:3], 0 op_sel_hi:[1, 0]
	v_lshlrev_b32_e32 v94, 16, v236
	v_and_b32_e32 v95, 0xffff0000, v236
	v_lshlrev_b32_e32 v84, 16, v237
	v_and_b32_e32 v85, 0xffff0000, v237
	v_pk_add_f32 v[88:89], v[88:89], v[84:85]
	v_lshlrev_b32_e32 v84, 16, v238
	v_and_b32_e32 v85, 0xffff0000, v238
	v_pk_add_f32 v[90:91], v[90:91], v[84:85]
	v_lshlrev_b32_e32 v86, 16, v239
	v_and_b32_e32 v87, 0xffff0000, v239
	v_pk_add_f32 v[92:93], v[92:93], v[86:87]
	v_pk_add_f32 v[2:3], v[2:3], v[94:95]
	s_mov_b32 s12, 0x62000
	v_lshlrev_b32_e32 v94, 16, v240
	v_and_b32_e32 v95, 0xffff0000, v240
	v_lshlrev_b32_e32 v84, 16, v241
	v_and_b32_e32 v85, 0xffff0000, v241
	v_pk_add_f32 v[94:95], v[2:3], v[94:95]
	v_lshlrev_b32_e32 v2, 16, v242
	v_and_b32_e32 v3, 0xffff0000, v242
	v_lshlrev_b32_e32 v86, 16, v243
	v_and_b32_e32 v87, 0xffff0000, v243
	v_pk_add_f32 v[84:85], v[88:89], v[84:85]
	v_pk_add_f32 v[88:89], v[92:93], v[86:87]
	v_pk_add_f32 v[2:3], v[90:91], v[2:3]
	v_lshlrev_b32_e32 v96, 16, v244
	v_and_b32_e32 v97, 0xffff0000, v244
	v_lshlrev_b32_e32 v86, 16, v245
	v_and_b32_e32 v87, 0xffff0000, v245
	v_pk_add_f32 v[86:87], v[84:85], v[86:87]
	v_pk_add_f32 v[84:85], v[94:95], v[96:97]
	v_lshlrev_b32_e32 v94, 16, v246
	v_and_b32_e32 v95, 0xffff0000, v246
	v_lshlrev_b32_e32 v90, 16, v247
	v_and_b32_e32 v91, 0xffff0000, v247
	v_pk_add_f32 v[90:91], v[88:89], v[90:91]
	v_pk_add_f32 v[88:89], v[2:3], v[94:95]
	s_and_b64 vcc, exec, s[10:11]
	s_cbranch_vccz .LBB0_417

.LBB0_417:
	v_add_co_u32_e32 v2, vcc, 0x2000, v124
	s_mov_b32 s12, 0x22000
	s_nop 0
	v_addc_co_u32_e32 v3, vcc, 0, v125, vcc
	global_load_dwordx4 v[232:235], v[2:3], off offset:3072
	v_add_co_u32_e32 v248, vcc, s12, v124
	s_nop 1
	v_addc_co_u32_e32 v249, vcc, 0, v125, vcc
	global_load_dwordx4 v[236:239], v[248:249], off offset:3072
	s_mov_b32 s98, 0x42000
	v_add_co_u32_e32 v248, vcc, s98, v124
	s_nop 1
	v_addc_co_u32_e32 v249, vcc, 0, v125, vcc
	global_load_dwordx4 v[240:243], v[248:249], off offset:3072
	s_mov_b32 s98, 0x62000
	v_add_co_u32_e32 v248, vcc, s98, v124
	s_nop 1
	v_addc_co_u32_e32 v249, vcc, 0, v125, vcc
	global_load_dwordx4 v[244:247], v[248:249], off offset:3072
	s_waitcnt vmcnt(0)
	v_lshlrev_b32_e32 v2, 16, v232
	v_and_b32_e32 v3, 0xffff0000, v232
	v_lshlrev_b32_e32 v92, 16, v233
	v_and_b32_e32 v93, 0xffff0000, v233
	v_pk_add_f32 v[96:97], v[92:93], 0 op_sel_hi:[1, 0]
	v_lshlrev_b32_e32 v92, 16, v234
	v_and_b32_e32 v93, 0xffff0000, v234
	v_pk_add_f32 v[98:99], v[92:93], 0 op_sel_hi:[1, 0]
	v_lshlrev_b32_e32 v94, 16, v235
	v_and_b32_e32 v95, 0xffff0000, v235
	v_pk_add_f32 v[100:101], v[94:95], 0 op_sel_hi:[1, 0]
	s_mov_b32 s12, 0x42000
	v_pk_add_f32 v[2:3], v[2:3], 0 op_sel_hi:[1, 0]
	v_lshlrev_b32_e32 v102, 16, v236
	v_and_b32_e32 v103, 0xffff0000, v236
	v_lshlrev_b32_e32 v92, 16, v237
	v_and_b32_e32 v93, 0xffff0000, v237
	v_pk_add_f32 v[96:97], v[96:97], v[92:93]
	v_lshlrev_b32_e32 v92, 16, v238
	v_and_b32_e32 v93, 0xffff0000, v238
	v_pk_add_f32 v[98:99], v[98:99], v[92:93]
	v_lshlrev_b32_e32 v94, 16, v239
	v_and_b32_e32 v95, 0xffff0000, v239
	v_pk_add_f32 v[100:101], v[100:101], v[94:95]
	v_pk_add_f32 v[2:3], v[2:3], v[102:103]
	s_mov_b32 s12, 0x62000
	v_lshlrev_b32_e32 v102, 16, v240
	v_and_b32_e32 v103, 0xffff0000, v240
	v_lshlrev_b32_e32 v92, 16, v241
	v_and_b32_e32 v93, 0xffff0000, v241
	v_pk_add_f32 v[102:103], v[2:3], v[102:103]
	v_lshlrev_b32_e32 v2, 16, v242
	v_and_b32_e32 v3, 0xffff0000, v242
	v_lshlrev_b32_e32 v94, 16, v243
	v_and_b32_e32 v95, 0xffff0000, v243
	v_pk_add_f32 v[92:93], v[96:97], v[92:93]
	v_pk_add_f32 v[96:97], v[100:101], v[94:95]
	v_pk_add_f32 v[2:3], v[98:99], v[2:3]
	v_lshlrev_b32_e32 v104, 16, v244
	v_and_b32_e32 v105, 0xffff0000, v244
	v_lshlrev_b32_e32 v94, 16, v245
	v_and_b32_e32 v95, 0xffff0000, v245
	v_pk_add_f32 v[94:95], v[92:93], v[94:95]
	v_pk_add_f32 v[92:93], v[102:103], v[104:105]
	v_lshlrev_b32_e32 v102, 16, v246
	v_and_b32_e32 v103, 0xffff0000, v246
	v_lshlrev_b32_e32 v98, 16, v247
	v_and_b32_e32 v99, 0xffff0000, v247
	v_pk_add_f32 v[98:99], v[96:97], v[98:99]
	v_pk_add_f32 v[96:97], v[2:3], v[102:103]
.LBB0_418:
	v_readlane_b32 s14, v255, 11
	v_readlane_b32 s15, v255, 12
	s_andn2_b64 vcc, exec, s[14:15]
	s_nop 0
	v_cndmask_b32_e64 v1, 0, 1, s[14:15]
	v_cmp_ne_u32_e64 s[12:13], 1, v1
	s_cbranch_vccnz .LBB0_423
	v_add_co_u32_e32 v2, vcc, 0x3000, v124
	s_nop 1
	v_addc_co_u32_e32 v3, vcc, 0, v125, vcc
	global_load_dwordx4 v[232:235], v[2:3], off
	v_add_co_u32_e32 v248, vcc, s45, v124
	s_nop 1
	v_addc_co_u32_e32 v249, vcc, 0, v125, vcc
	global_load_dwordx4 v[236:239], v[248:249], off
	v_add_co_u32_e32 v248, vcc, s57, v124
	s_nop 1
	v_addc_co_u32_e32 v249, vcc, 0, v125, vcc
	global_load_dwordx4 v[240:243], v[248:249], off
	v_add_co_u32_e32 v248, vcc, s85, v124
	s_nop 1
	v_addc_co_u32_e32 v249, vcc, 0, v125, vcc
	global_load_dwordx4 v[244:247], v[248:249], off
	s_waitcnt vmcnt(0)
	v_lshlrev_b32_e32 v2, 16, v232
	v_and_b32_e32 v3, 0xffff0000, v232
	v_lshlrev_b32_e32 v100, 16, v233
	v_and_b32_e32 v101, 0xffff0000, v233
	v_pk_add_f32 v[104:105], v[100:101], 0 op_sel_hi:[1, 0]
	v_lshlrev_b32_e32 v100, 16, v234
	v_and_b32_e32 v101, 0xffff0000, v234
	v_pk_add_f32 v[106:107], v[100:101], 0 op_sel_hi:[1, 0]
	v_lshlrev_b32_e32 v102, 16, v235
	v_and_b32_e32 v103, 0xffff0000, v235
	v_pk_add_f32 v[108:109], v[102:103], 0 op_sel_hi:[1, 0]
	v_pk_add_f32 v[2:3], v[2:3], 0 op_sel_hi:[1, 0]
	v_lshlrev_b32_e32 v110, 16, v236
	v_and_b32_e32 v111, 0xffff0000, v236
	v_lshlrev_b32_e32 v100, 16, v237
	v_and_b32_e32 v101, 0xffff0000, v237
	v_pk_add_f32 v[104:105], v[104:105], v[100:101]
	v_lshlrev_b32_e32 v100, 16, v238
	v_and_b32_e32 v101, 0xffff0000, v238
	v_pk_add_f32 v[106:107], v[106:107], v[100:101]
	v_lshlrev_b32_e32 v102, 16, v239
	v_and_b32_e32 v103, 0xffff0000, v239
	v_pk_add_f32 v[108:109], v[108:109], v[102:103]
	v_pk_add_f32 v[2:3], v[2:3], v[110:111]
	v_lshlrev_b32_e32 v110, 16, v240
	v_and_b32_e32 v111, 0xffff0000, v240
	v_lshlrev_b32_e32 v100, 16, v241
	v_and_b32_e32 v101, 0xffff0000, v241
	v_pk_add_f32 v[110:111], v[2:3], v[110:111]
	v_lshlrev_b32_e32 v2, 16, v242
	v_and_b32_e32 v3, 0xffff0000, v242
	v_lshlrev_b32_e32 v102, 16, v243
	v_and_b32_e32 v103, 0xffff0000, v243
	v_pk_add_f32 v[100:101], v[104:105], v[100:101]
	v_pk_add_f32 v[104:105], v[108:109], v[102:103]
	v_pk_add_f32 v[2:3], v[106:107], v[2:3]
	v_lshlrev_b32_e32 v112, 16, v244
	v_and_b32_e32 v113, 0xffff0000, v244
	v_lshlrev_b32_e32 v102, 16, v245
	v_and_b32_e32 v103, 0xffff0000, v245
	v_pk_add_f32 v[102:103], v[100:101], v[102:103]
	v_pk_add_f32 v[100:101], v[110:111], v[112:113]
	v_lshlrev_b32_e32 v110, 16, v246
	v_and_b32_e32 v111, 0xffff0000, v246
	v_lshlrev_b32_e32 v106, 16, v247
	v_and_b32_e32 v107, 0xffff0000, v247
	v_pk_add_f32 v[106:107], v[104:105], v[106:107]
	v_pk_add_f32 v[104:105], v[2:3], v[110:111]
	s_and_b64 vcc, exec, s[12:13]
	s_cbranch_vccz .LBB0_424

.LBB0_424:
	v_add_co_u32_e32 v2, vcc, 0x3000, v124
	s_nop 1
	v_addc_co_u32_e32 v3, vcc, 0, v125, vcc
	global_load_dwordx4 v[232:235], v[2:3], off offset:1024
	v_add_co_u32_e32 v248, vcc, s45, v124
	s_nop 1
	v_addc_co_u32_e32 v249, vcc, 0, v125, vcc
	global_load_dwordx4 v[236:239], v[248:249], off offset:1024
	v_add_co_u32_e32 v248, vcc, s57, v124
	s_nop 1
	v_addc_co_u32_e32 v249, vcc, 0, v125, vcc
	global_load_dwordx4 v[240:243], v[248:249], off offset:1024
	v_add_co_u32_e32 v248, vcc, s85, v124
	s_nop 1
	v_addc_co_u32_e32 v249, vcc, 0, v125, vcc
	global_load_dwordx4 v[244:247], v[248:249], off offset:1024
	s_waitcnt vmcnt(0)
	v_lshlrev_b32_e32 v2, 16, v232
	v_and_b32_e32 v3, 0xffff0000, v232
	v_lshlrev_b32_e32 v108, 16, v233
	v_and_b32_e32 v109, 0xffff0000, v233
	v_pk_add_f32 v[112:113], v[108:109], 0 op_sel_hi:[1, 0]
	v_lshlrev_b32_e32 v108, 16, v234
	v_and_b32_e32 v109, 0xffff0000, v234
	v_pk_add_f32 v[114:115], v[108:109], 0 op_sel_hi:[1, 0]
	v_lshlrev_b32_e32 v110, 16, v235
	v_and_b32_e32 v111, 0xffff0000, v235
	v_pk_add_f32 v[116:117], v[110:111], 0 op_sel_hi:[1, 0]
	v_pk_add_f32 v[2:3], v[2:3], 0 op_sel_hi:[1, 0]
	v_lshlrev_b32_e32 v118, 16, v236
	v_and_b32_e32 v119, 0xffff0000, v236
	v_lshlrev_b32_e32 v108, 16, v237
	v_and_b32_e32 v109, 0xffff0000, v237
	v_pk_add_f32 v[112:113], v[112:113], v[108:109]
	v_lshlrev_b32_e32 v108, 16, v238
	v_and_b32_e32 v109, 0xffff0000, v238
	v_pk_add_f32 v[114:115], v[114:115], v[108:109]
	v_lshlrev_b32_e32 v110, 16, v239
	v_and_b32_e32 v111, 0xffff0000, v239
	v_pk_add_f32 v[116:117], v[116:117], v[110:111]
	v_pk_add_f32 v[2:3], v[2:3], v[118:119]
	v_lshlrev_b32_e32 v118, 16, v240
	v_and_b32_e32 v119, 0xffff0000, v240
	v_lshlrev_b32_e32 v108, 16, v241
	v_and_b32_e32 v109, 0xffff0000, v241
	v_pk_add_f32 v[118:119], v[2:3], v[118:119]
	v_lshlrev_b32_e32 v2, 16, v242
	v_and_b32_e32 v3, 0xffff0000, v242
	v_lshlrev_b32_e32 v110, 16, v243
	v_and_b32_e32 v111, 0xffff0000, v243
	v_pk_add_f32 v[108:109], v[112:113], v[108:109]
	v_pk_add_f32 v[112:113], v[116:117], v[110:111]
	v_pk_add_f32 v[2:3], v[114:115], v[2:3]
	v_lshlrev_b32_e32 v120, 16, v244
	v_and_b32_e32 v121, 0xffff0000, v244
	v_lshlrev_b32_e32 v110, 16, v245
	v_and_b32_e32 v111, 0xffff0000, v245
	v_pk_add_f32 v[110:111], v[108:109], v[110:111]
	v_pk_add_f32 v[108:109], v[118:119], v[120:121]
	v_lshlrev_b32_e32 v118, 16, v246
	v_and_b32_e32 v119, 0xffff0000, v246
	v_lshlrev_b32_e32 v114, 16, v247
	v_and_b32_e32 v115, 0xffff0000, v247
	v_pk_add_f32 v[114:115], v[112:113], v[114:115]
	v_pk_add_f32 v[112:113], v[2:3], v[118:119]
	s_and_b64 vcc, exec, s[8:9]
	s_cbranch_vccnz .LBB0_421
.LBB0_425:
	v_add_co_u32_e32 v2, vcc, 0x3000, v124
	s_nop 1
	v_addc_co_u32_e32 v3, vcc, 0, v125, vcc
	global_load_dwordx4 v[232:235], v[2:3], off offset:2048
	v_add_co_u32_e32 v248, vcc, s45, v124
	s_nop 1
	v_addc_co_u32_e32 v249, vcc, 0, v125, vcc
	global_load_dwordx4 v[236:239], v[248:249], off offset:2048
	v_add_co_u32_e32 v248, vcc, s57, v124
	s_nop 1
	v_addc_co_u32_e32 v249, vcc, 0, v125, vcc
	global_load_dwordx4 v[240:243], v[248:249], off offset:2048
	v_add_co_u32_e32 v248, vcc, s85, v124
	s_nop 1
	v_addc_co_u32_e32 v249, vcc, 0, v125, vcc
	global_load_dwordx4 v[244:247], v[248:249], off offset:2048
	s_waitcnt vmcnt(0)
	v_lshlrev_b32_e32 v2, 16, v232
	v_and_b32_e32 v3, 0xffff0000, v232
	v_lshlrev_b32_e32 v116, 16, v233
	v_and_b32_e32 v117, 0xffff0000, v233
	v_pk_add_f32 v[120:121], v[116:117], 0 op_sel_hi:[1, 0]
	v_lshlrev_b32_e32 v116, 16, v234
	v_and_b32_e32 v117, 0xffff0000, v234
	v_pk_add_f32 v[122:123], v[116:117], 0 op_sel_hi:[1, 0]
	v_lshlrev_b32_e32 v118, 16, v235
	v_and_b32_e32 v119, 0xffff0000, v235
	v_pk_add_f32 v[126:127], v[118:119], 0 op_sel_hi:[1, 0]
	v_pk_add_f32 v[2:3], v[2:3], 0 op_sel_hi:[1, 0]
	v_lshlrev_b32_e32 v128, 16, v236
	v_and_b32_e32 v129, 0xffff0000, v236
	v_lshlrev_b32_e32 v116, 16, v237
	v_and_b32_e32 v117, 0xffff0000, v237
	v_pk_add_f32 v[120:121], v[120:121], v[116:117]
	v_lshlrev_b32_e32 v116, 16, v238
	v_and_b32_e32 v117, 0xffff0000, v238
	v_pk_add_f32 v[122:123], v[122:123], v[116:117]
	v_lshlrev_b32_e32 v118, 16, v239
	v_and_b32_e32 v119, 0xffff0000, v239
	v_pk_add_f32 v[126:127], v[126:127], v[118:119]
	v_pk_add_f32 v[2:3], v[2:3], v[128:129]
	v_lshlrev_b32_e32 v128, 16, v240
	v_and_b32_e32 v129, 0xffff0000, v240
	v_lshlrev_b32_e32 v116, 16, v241
	v_and_b32_e32 v117, 0xffff0000, v241
	v_pk_add_f32 v[130:131], v[2:3], v[128:129]
	v_lshlrev_b32_e32 v2, 16, v242
	v_and_b32_e32 v3, 0xffff0000, v242
	v_lshlrev_b32_e32 v118, 16, v243
	v_and_b32_e32 v119, 0xffff0000, v243
	v_pk_add_f32 v[116:117], v[120:121], v[116:117]
	v_pk_add_f32 v[120:121], v[126:127], v[118:119]
	v_pk_add_f32 v[2:3], v[122:123], v[2:3]
	v_lshlrev_b32_e32 v122, 16, v244
	v_and_b32_e32 v123, 0xffff0000, v244
	v_lshlrev_b32_e32 v118, 16, v245
	v_and_b32_e32 v119, 0xffff0000, v245
	v_pk_add_f32 v[118:119], v[116:117], v[118:119]
	v_pk_add_f32 v[116:117], v[130:131], v[122:123]
	v_lshlrev_b32_e32 v126, 16, v246
	v_and_b32_e32 v127, 0xffff0000, v246
	v_lshlrev_b32_e32 v122, 16, v247
	v_and_b32_e32 v123, 0xffff0000, v247
	v_pk_add_f32 v[122:123], v[120:121], v[122:123]
	v_pk_add_f32 v[120:121], v[2:3], v[126:127]
	s_and_b64 vcc, exec, s[8:9]
	s_cbranch_vccnz .LBB0_422
.LBB0_426:
	v_add_co_u32_e32 v2, vcc, 0x3000, v124
	s_nop 1
	v_addc_co_u32_e32 v3, vcc, 0, v125, vcc
	global_load_dwordx4 v[232:235], v[2:3], off offset:3072
	v_add_co_u32_e32 v248, vcc, s45, v124
	s_nop 1
	v_addc_co_u32_e32 v249, vcc, 0, v125, vcc
	global_load_dwordx4 v[236:239], v[248:249], off offset:3072
	v_add_co_u32_e32 v248, vcc, s57, v124
	s_nop 1
	v_addc_co_u32_e32 v249, vcc, 0, v125, vcc
	global_load_dwordx4 v[240:243], v[248:249], off offset:3072
	v_add_co_u32_e32 v248, vcc, s85, v124
	s_nop 1
	v_addc_co_u32_e32 v249, vcc, 0, v125, vcc
	global_load_dwordx4 v[244:247], v[248:249], off offset:3072
	s_waitcnt vmcnt(0)
	v_lshlrev_b32_e32 v2, 16, v232
	v_and_b32_e32 v3, 0xffff0000, v232
	v_lshlrev_b32_e32 v126, 16, v233
	v_and_b32_e32 v127, 0xffff0000, v233
	v_pk_add_f32 v[130:131], v[126:127], 0 op_sel_hi:[1, 0]
	v_lshlrev_b32_e32 v126, 16, v234
	v_and_b32_e32 v127, 0xffff0000, v234
	v_pk_add_f32 v[132:133], v[126:127], 0 op_sel_hi:[1, 0]
	v_lshlrev_b32_e32 v128, 16, v235
	v_and_b32_e32 v129, 0xffff0000, v235
	v_pk_add_f32 v[134:135], v[128:129], 0 op_sel_hi:[1, 0]
	v_pk_add_f32 v[2:3], v[2:3], 0 op_sel_hi:[1, 0]
	v_lshlrev_b32_e32 v136, 16, v236
	v_and_b32_e32 v137, 0xffff0000, v236
	v_lshlrev_b32_e32 v126, 16, v237
	v_and_b32_e32 v127, 0xffff0000, v237
	v_pk_add_f32 v[130:131], v[130:131], v[126:127]
	v_lshlrev_b32_e32 v126, 16, v238
	v_and_b32_e32 v127, 0xffff0000, v238
	v_pk_add_f32 v[132:133], v[132:133], v[126:127]
	v_lshlrev_b32_e32 v128, 16, v239
	v_and_b32_e32 v129, 0xffff0000, v239
	v_pk_add_f32 v[134:135], v[134:135], v[128:129]
	v_pk_add_f32 v[2:3], v[2:3], v[136:137]
	v_lshlrev_b32_e32 v136, 16, v240
	v_and_b32_e32 v137, 0xffff0000, v240
	v_lshlrev_b32_e32 v126, 16, v241
	v_and_b32_e32 v127, 0xffff0000, v241
	v_pk_add_f32 v[136:137], v[2:3], v[136:137]
	v_lshlrev_b32_e32 v2, 16, v242
	v_and_b32_e32 v3, 0xffff0000, v242
	v_pk_add_f32 v[126:127], v[130:131], v[126:127]
	v_pk_add_f32 v[2:3], v[132:133], v[2:3]
	v_lshlrev_b32_e32 v128, 16, v243
	v_and_b32_e32 v129, 0xffff0000, v243
	v_pk_add_f32 v[128:129], v[134:135], v[128:129]
	v_lshlrev_b32_e32 v124, 16, v244
	v_and_b32_e32 v125, 0xffff0000, v244
	v_lshlrev_b32_e32 v130, 16, v245
	v_and_b32_e32 v131, 0xffff0000, v245
	v_pk_add_f32 v[126:127], v[126:127], v[130:131]
	v_lshlrev_b32_e32 v134, 16, v246
	v_and_b32_e32 v135, 0xffff0000, v246
	v_lshlrev_b32_e32 v130, 16, v247
	v_and_b32_e32 v131, 0xffff0000, v247
	v_pk_add_f32 v[124:125], v[136:137], v[124:125]
	v_pk_add_f32 v[130:131], v[128:129], v[130:131]
	v_pk_add_f32 v[128:129], v[2:3], v[134:135]
